# load balance: Fourier step-A / step-B tile lists rotated by 448 half-blocks so the extra tiles do not land on the half-blocks that already own a fifth RG-LRU tile
# baseline (speedup 1.0000x reference)
; __device__ __forceinline__ void fourier_stepA_tile(const Params& P, int t, u16* smem) {
;   const int mt = t >> 3, grp = t & 7;
;   const u16* Ab = P.zq + (long)mt * 128 * 1536 + 1024 + grp * 64;
;   const u16* Bb = P.d64t;
;   auto al = [=](int r, int k) { return ldg16(Ab + (unsigned)(r * 1536 + k)); };
;   auto bl = [=](int r, int k) { return ldg16(Bb + r * 64 + k); };
;   f32x16 acc[2][2];
;   gemm_tile<false>(al, bl, 64, smem, acc);
; __device__ __forceinline__ void run_phase(const Params& P, const int ph, char* smem_raw) {
;     ...
;       for (int t = VBID; t < 2112; t += VGRID) lru_tile(P, t >> 3, t & 7, 1, smv_raw);
;       for (int t = VBID; t < 2112; t += VGRID) fourier_stepA_tile(P, t, smv);
.LBB0_417:
	s_or_b64 exec, exec, s[8:9]
	v_add_u32_e32 v86, 0x1c0, v86
	v_and_b32_e32 v86, 0x1ff, v86
	v_mul_u32_u24_e32 v1, 0x600, v72
	s_movk_i32 s0, 0x48
	v_or_b32_e32 v8, v1, v48
	v_mad_u32_u24 v1, v69, s0, v48
	v_and_b32_e32 v3, 8, v66
	v_lshl_add_u32 v89, v1, 1, v49
	v_and_b32_e32 v1, 31, v152
	v_lshlrev_b32_e32 v3, 1, v3
	v_and_or_b32 v1, v64, 64, v1
	v_add_u32_e32 v5, v49, v3
	s_movk_i32 s0, 0x90
	v_mov_b32_e32 v65, 0
	v_lshlrev_b32_e32 v4, 7, v69
	v_mad_u32_u24 v90, v1, s0, v5
	v_and_b32_e32 v1, 0x5f, v152
	v_lshlrev_b32_e32 v64, 1, v48
	v_mul_u32_u24_e32 v0, 0x600, v69
	v_mul_u32_u24_e32 v1, 0x48, v1
	v_lshl_add_u64 v[10:11], s[42:43], 0, v[64:65]
	v_or_b32_e32 v64, 0x1000, v4
	v_or_b32_e32 v0, v0, v48
	v_lshlrev_b32_e32 v1, 1, v1
	v_lshl_add_u64 v[68:69], v[10:11], 0, v[64:65]
	v_or_b32_e32 v64, 0x2000, v4
	v_add_u32_e32 v2, 0xc000, v0
	v_add_u32_e32 v6, 0x18000, v0
	v_add3_u32 v91, v49, v1, v3
	v_add_u32_e32 v92, v5, v1
	v_mov_b32_e32 v5, v65
	v_lshl_add_u64 v[70:71], v[10:11], 0, v[64:65]
	v_lshlrev_b32_e32 v64, 7, v72
	s_add_u32 s0, s90, 0x6300000
	v_lshlrev_b32_e32 v1, 6, v153
	v_lshl_add_u64 v[66:67], v[10:11], 0, v[4:5]
	v_lshl_add_u64 v[72:73], v[10:11], 0, v[64:65]
	s_addc_u32 s1, s91, 0
	v_lshl_add_u32 v93, s2, 7, v1
	s_lshl_b32 s8, s96, 7
	s_mov_b64 s[4:5], 0
	s_mov_b32 s9, 0x60000
	v_mov_b64_e32 v[74:75], s[90:91]
	v_lshlrev_b32_e32 v76, 1, v0
	v_mov_b32_e32 v77, v65
	v_lshlrev_b32_e32 v78, 1, v2
	v_mov_b32_e32 v79, v65
	v_lshlrev_b32_e32 v80, 1, v6
	v_mov_b32_e32 v81, v65
	v_lshlrev_b32_e32 v82, 1, v8
	v_mov_b32_e32 v83, v65
	s_movk_i32 s10, 0x200
	s_mov_b32 s11, 0x3fffc0
	s_movk_i32 s12, 0x83f

; __device__ __forceinline__ void nn_phase(const Params& P, int set, u16* smem) {
;   const int nT = (set == 0) ? 2080 : 1024;
;   for (int t = VBID; t < nT; t += VGRID) {
;     const u16 *Ab, *Bb; u16* Cb; unsigned lda, s1, s2, e1, e2; int K;
;     const u16* G = P.zq + (long)N_TOK * 1536;
;     const int nt = t & 3;
;     if (set == 0 && t < 2048) {
; __device__ __forceinline__ void run_phase(const Params& P, const int ph, char* smem_raw) {
;     ...
;       for (int t = VBID; t < 2112; t += VGRID) lru_tile(P, t >> 3, t & 7, 2, smv_raw);
;       nn_phase(P, 0, smv);
.LBB0_680:
	s_or_b64 exec, exec, s[16:17]
	v_add_u32_e32 v74, 0x1c0, v74
	v_and_b32_e32 v74, 0x1ff, v74
	s_movk_i32 s0, 0x820
	v_cmp_gt_i32_e32 vcc, s0, v74
	s_and_saveexec_b64 s[0:1], vcc
	s_cbranch_execz .LBB0_689
	v_lshrrev_b32_e32 v0, 3, v152
	v_lshlrev_b32_e32 v1, 3, v152
	v_or_b32_e32 v79, 0x60, v0
	v_lshrrev_b32_e32 v0, 1, v152
	v_and_b32_e32 v2, 31, v152
	v_and_b32_e32 v76, 56, v1
	v_lshrrev_b32_e32 v1, 4, v152
	v_and_or_b32 v0, v0, 64, v2
	v_lshrrev_b32_e32 v2, 2, v152
	v_bfe_u32 v75, v152, 3, 5
	v_and_b32_e32 v77, 0x7f, v152
	v_and_b32_e32 v1, 8, v1
	s_movk_i32 s3, 0x48
	v_and_b32_e32 v2, 8, v2
	v_mad_u32_u24 v80, v77, s3, v1
	v_mad_u32_u24 v81, v75, s3, v76
	v_mad_u32_u24 v84, v79, s3, v76
	v_and_b32_e32 v3, 0x5f, v152
	v_mad_u32_u24 v86, v0, s3, v2
	s_add_u32 s4, s90, 0x6300000
	s_movk_i32 s8, 0x8000
	v_lshrrev_b32_e32 v78, 1, v1
	v_lshl_add_u32 v82, v81, 1, v71
	v_lshl_add_u32 v83, v80, 1, v71
	v_lshl_add_u32 v85, v84, 1, v71
	v_mad_u32_u24 v87, v3, s3, v2
	v_and_b32_e32 v88, 0xff, v152
	s_addc_u32 s5, s91, 0
	s_lshl_b32 s3, s96, 1
	v_add_u32_e32 v89, 16, v86
	v_add_u32_e32 v90, 32, v86
	v_add_u32_e32 v91, 48, v86
	v_or_b32_e32 v92, 64, v1
	v_or_b32_e32 v93, 64, v76
	s_mov_b64 s[6:7], 0
	s_movk_i32 s14, 0x7ff
	v_mov_b32_e32 v65, 0
	s_mov_b32 s9, -1
	s_mov_b64 s[10:11], 0x400
	s_movk_i32 s15, 0x81f
